# T9 + odd-layer PEER LayerNorm epilogue gamma/beta loads pipelined (as the even-layer copy)
# baseline (speedup 1.0000x reference)
; #define GAS __attribute__((address_space(1)))
; __device__ __forceinline__ void peer_gather_f4p(const float* X, const int* __restrict__ IDX, const float* __restrict__ G, ...
;     ...
;         asm volatile("" : "+v"(lane));
;         f32x2 xr[16];
; #pragma unroll
;         for (int j = 0; j < 8; ++j) {
;             if (RES_BF16) {
;                 const u32x2 t2 = *(const GAS u32x2*)((const GAS bf16_t*)xbout + (size_t)row * D + 256 * j + lane * 4);
;                 xr[2 * j] = f32x2{__uint_as_float(t2[0] << 16), __uint_as_float(t2[0] & 0xffff0000u)}; xr[2 * j + 1] = f32x2{__uint_as_float(t2[1] << 16), __uint_as_float(t2[1] & 0xffff0000u)};
;             } else {
;                 const f32x4 t4 = *(const GAS f32x4*)((const GAS float*)X + (size_t)row * D + 256 * j + lane * 4);
;                 xr[2 * j] = f32x2{t4[0], t4[1]}; xr[2 * j + 1] = f32x2{t4[2], t4[3]};
;             }
;         }
;         float s1 = 0.f;
; #pragma unroll
;         for (int k = 0; k < 16; ++k) { acc[k][0] = fmaf(ALPHA, xr[k][0], acc[k][0]); acc[k][1] = fmaf(ALPHA, xr[k][1], acc[k][1]); s1 += acc[k][0] + acc[k][1]; }
;         const float mu = wsum(s1) * (1.f / D);
;         float s2 = 0.f;
; #pragma unroll
;         for (int k = 0; k < 16; ++k) { const float d0 = acc[k][0] - mu, d1 = acc[k][1] - mu; s2 = fmaf(d0, d0, s2); s2 = fmaf(d1, d1, s2); }
;         const float rstd = rsqrtf(wsum(s2) * (1.f / D) + LN_EPS);
;         const float* gl_ = g; const float* bl_ = bb;
;         asm volatile("" : "+s"(gl_), "+s"(bl_));
; #pragma unroll
;         for (int j = 0; j < 8; ++j) {
;             const int col = 256 * j + lane * 4;
;             const f32x4 g4 = *(const GAS f32x4*)((const GAS float*)gl_ + col), b4 = *(const GAS f32x4*)((const GAS float*)bl_ + col);
.LBB0_1252:
	s_add_i32 s42, s19, s56
	s_ashr_i32 s43, s42, 31
	s_lshl_b64 s[16:17], s[42:43], 12
	s_add_u32 s16, s15, s16
	s_waitcnt vmcnt(13)
	v_lshlrev_b32_e32 v14, 2, v2
	s_addc_u32 s17, s18, s17
	v_ashrrev_i32_e32 v15, 31, v14
	v_lshl_add_u64 v[8:9], v[14:15], 1, s[16:17]
	global_load_dwordx2 v[4:5], v[8:9], off offset:3584
	global_load_dwordx2 v[6:7], v[8:9], off offset:3072
	global_load_dwordx2 v[10:11], v[8:9], off offset:2560
	global_load_dwordx2 v[12:13], v[8:9], off offset:2048
	global_load_dwordx2 v[16:17], v[8:9], off offset:1536
	global_load_dwordx2 v[18:19], v[8:9], off offset:1024
	global_load_dwordx2 v[20:21], v[8:9], off offset:512
	global_load_dwordx2 v[22:23], v[8:9], off
	s_mov_b64 s[16:17], s[44:45]
	s_mov_b64 s[26:27], s[46:47]
	s_waitcnt vmcnt(7)
	v_lshlrev_b32_e32 v24, 16, v5
	v_and_b32_e32 v25, 0xffff0000, v5
	v_lshlrev_b32_e32 v26, 16, v4
	v_and_b32_e32 v27, 0xffff0000, v4
	s_waitcnt vmcnt(6)
	v_lshlrev_b32_e32 v4, 16, v7
	v_and_b32_e32 v5, 0xffff0000, v7
	v_lshlrev_b32_e32 v28, 16, v6
	s_waitcnt vmcnt(0)
	v_lshlrev_b32_e32 v40, 16, v22
	v_and_b32_e32 v41, 0xffff0000, v22
	v_and_b32_e32 v29, 0xffff0000, v6
	v_lshlrev_b32_e32 v6, 16, v11
	v_and_b32_e32 v7, 0xffff0000, v11
	v_lshlrev_b32_e32 v30, 16, v10
	v_and_b32_e32 v31, 0xffff0000, v10
	v_lshlrev_b32_e32 v10, 16, v13
	v_and_b32_e32 v11, 0xffff0000, v13
	v_lshlrev_b32_e32 v32, 16, v12
	v_and_b32_e32 v33, 0xffff0000, v12
	v_lshlrev_b32_e32 v12, 16, v17
	v_and_b32_e32 v13, 0xffff0000, v17
	v_lshlrev_b32_e32 v34, 16, v16
	v_and_b32_e32 v35, 0xffff0000, v16
	v_lshlrev_b32_e32 v16, 16, v19
	v_and_b32_e32 v17, 0xffff0000, v19
	v_lshlrev_b32_e32 v36, 16, v18
	v_and_b32_e32 v37, 0xffff0000, v18
	v_lshlrev_b32_e32 v18, 16, v21
	v_and_b32_e32 v19, 0xffff0000, v21
	v_lshlrev_b32_e32 v38, 16, v20
	v_and_b32_e32 v39, 0xffff0000, v20
	v_lshlrev_b32_e32 v20, 16, v23
	v_and_b32_e32 v21, 0xffff0000, v23
	v_pk_fma_f32 v[40:41], v[40:41], s[2:3], v[166:167] op_sel_hi:[1,0,1]
	v_pk_fma_f32 v[20:21], v[20:21], s[2:3], v[168:169] op_sel_hi:[1,0,1]
	v_add_f32_e32 v48, v41, v40
	v_pk_fma_f32 v[38:39], v[38:39], s[2:3], v[170:171] op_sel_hi:[1,0,1]
	v_add_f32_e32 v47, v21, v20
	v_add_f32_e32 v48, 0, v48
	v_pk_fma_f32 v[18:19], v[18:19], s[2:3], v[172:173] op_sel_hi:[1,0,1]
	v_add_f32_e32 v46, v39, v38
	v_add_f32_e32 v47, v47, v48
	v_pk_fma_f32 v[36:37], v[36:37], s[2:3], v[174:175] op_sel_hi:[1,0,1]
	v_add_f32_e32 v45, v19, v18
	v_add_f32_e32 v46, v46, v47
	v_pk_fma_f32 v[16:17], v[16:17], s[2:3], v[176:177] op_sel_hi:[1,0,1]
	v_add_f32_e32 v44, v37, v36
	v_add_f32_e32 v45, v45, v46
	v_pk_fma_f32 v[34:35], v[34:35], s[2:3], v[178:179] op_sel_hi:[1,0,1]
	v_add_f32_e32 v43, v17, v16
	v_add_f32_e32 v44, v44, v45
	v_pk_fma_f32 v[50:51], v[26:27], s[2:3], v[194:195] op_sel_hi:[1,0,1]
	v_pk_fma_f32 v[26:27], v[30:31], s[2:3], v[186:187] op_sel_hi:[1,0,1]
	v_pk_fma_f32 v[30:31], v[32:33], s[2:3], v[182:183] op_sel_hi:[1,0,1]
	v_pk_fma_f32 v[32:33], v[12:13], s[2:3], v[180:181] op_sel_hi:[1,0,1]
	v_add_f32_e32 v42, v35, v34
	v_add_f32_e32 v43, v43, v44
	v_add_f32_e32 v13, v33, v32
	v_add_f32_e32 v42, v42, v43
	v_pk_fma_f32 v[54:55], v[10:11], s[2:3], v[184:185] op_sel_hi:[1,0,1]
	v_add_f32_e32 v12, v31, v30
	v_add_f32_e32 v13, v13, v42
	v_add_f32_e32 v11, v55, v54
	v_add_f32_e32 v12, v12, v13
	v_pk_fma_f32 v[52:53], v[28:29], s[2:3], v[190:191] op_sel_hi:[1,0,1]
	v_pk_fma_f32 v[28:29], v[6:7], s[2:3], v[188:189] op_sel_hi:[1,0,1]
	v_add_f32_e32 v10, v27, v26
	v_add_f32_e32 v11, v11, v12
	v_add_f32_e32 v7, v29, v28
	v_add_f32_e32 v10, v10, v11
	v_pk_fma_f32 v[22:23], v[4:5], s[2:3], v[192:193] op_sel_hi:[1,0,1]
	v_add_f32_e32 v6, v53, v52
	v_add_f32_e32 v7, v7, v10
	v_add_f32_e32 v5, v23, v22
	v_add_f32_e32 v6, v6, v7
	v_pk_fma_f32 v[24:25], v[24:25], s[2:3], v[196:197] op_sel_hi:[1,0,1]
	v_add_f32_e32 v4, v51, v50
	v_add_f32_e32 v5, v5, v6
	v_add_f32_e32 v2, v25, v24
	v_add_f32_e32 v4, v4, v5
	v_add_f32_e32 v2, v2, v4
	ds_swizzle_b32 v4, v2 offset:swizzle(SWAP,1)
	s_waitcnt lgkmcnt(0)
	v_add_f32_e32 v2, v2, v4
	ds_swizzle_b32 v4, v2 offset:swizzle(SWAP,2)
	s_waitcnt lgkmcnt(0)
	v_add_f32_e32 v2, v2, v4
	ds_swizzle_b32 v4, v2 offset:swizzle(SWAP,4)
	s_waitcnt lgkmcnt(0)
	v_add_f32_e32 v2, v2, v4
	ds_swizzle_b32 v6, v2 offset:swizzle(SWAP,8)
	v_lshlrev_b64 v[4:5], 2, v[14:15]
	v_lshl_add_u64 v[12:13], s[16:17], 0, v[4:5]
	v_lshl_add_u64 v[10:11], s[26:27], 0, v[4:5]
	s_lshl_b64 s[16:17], s[42:43], 13
	s_waitcnt lgkmcnt(0)
	v_add_f32_e32 v2, v2, v6
	ds_swizzle_b32 v42, v2 offset:swizzle(SWAP,16)
	global_load_dwordx4 v[4:7], v[12:13], off
	global_load_dwordx4 v[46:49], v[10:11], off
	s_add_u32 s16, s78, s16
	s_addc_u32 s17, s79, s17
	s_andn2_b64 vcc, exec, s[48:49]
	s_waitcnt lgkmcnt(0)
; #define GAS __attribute__((address_space(1)))
; __device__ __forceinline__ unsigned cvtpk(float lo, float hi) { return __builtin_bit_cast(unsigned, __builtin_convertvector(f32x2_cv{lo, hi}, bf16x2_cv)); }
; __device__ __forceinline__ void peer_gather_f4p(const float* X, const int* __restrict__ IDX, const float* __restrict__ G, ...
;     ...
;         for (int k = 0; k < 16; ++k) { acc[k][0] = fmaf(ALPHA, xr[k][0], acc[k][0]); acc[k][1] = fmaf(ALPHA, xr[k][1], acc[k][1]); s1 += acc[k][0] + acc[k][1]; }
;         const float mu = wsum(s1) * (1.f / D);
;         float s2 = 0.f;
; #pragma unroll
;         for (int k = 0; k < 16; ++k) { const float d0 = acc[k][0] - mu, d1 = acc[k][1] - mu; s2 = fmaf(d0, d0, s2); s2 = fmaf(d1, d1, s2); }
;         const float rstd = rsqrtf(wsum(s2) * (1.f / D) + LN_EPS);
;         const float* gl_ = g; const float* bl_ = bb;
;         asm volatile("" : "+s"(gl_), "+s"(bl_));
; #pragma unroll
;         for (int j = 0; j < 8; ++j) {
;             const int col = 256 * j + lane * 4;
;             const f32x4 g4 = *(const GAS f32x4*)((const GAS float*)gl_ + col), b4 = *(const GAS f32x4*)((const GAS float*)bl_ + col);
;             f32x4 o4;
;             o4[0] = (acc[2 * j][0] - mu) * rstd * g4[0] + b4[0]; o4[1] = (acc[2 * j][1] - mu) * rstd * g4[1] + b4[1];
;             o4[2] = (acc[2 * j + 1][0] - mu) * rstd * g4[2] + b4[2]; o4[3] = (acc[2 * j + 1][1] - mu) * rstd * g4[3] + b4[3];
;             if (!RES_BF16 || dst != nullptr) *(GAS f32x4*)((GAS float*)dst + (size_t)row * D + col) = o4;
;             *(GAS u32x2*)((GAS bf16_t*)xbout + (size_t)row * D + col) = u32x2{cvtpk(o4[0], o4[1]), cvtpk(o4[2], o4[3])};
;         }
	v_add_f32_e32 v2, v2, v42
	v_mov_b32_e32 v42, v2
	s_nop 1
	v_permlane32_swap_b32_e32 v2, v42
	v_add_f32_e32 v2, v2, v42
	v_mul_f32_e32 v2, 0x3a000000, v2
	v_pk_add_f32 v[56:57], v[40:41], v[2:3] op_sel_hi:[1,0] neg_lo:[0,1] neg_hi:[0,1]
	v_pk_add_f32 v[58:59], v[20:21], v[2:3] op_sel_hi:[1,0] neg_lo:[0,1] neg_hi:[0,1]
	v_pk_add_f32 v[42:43], v[38:39], v[2:3] op_sel_hi:[1,0] neg_lo:[0,1] neg_hi:[0,1]
	v_pk_add_f32 v[44:45], v[18:19], v[2:3] op_sel_hi:[1,0] neg_lo:[0,1] neg_hi:[0,1]
	v_pk_add_f32 v[38:39], v[36:37], v[2:3] op_sel_hi:[1,0] neg_lo:[0,1] neg_hi:[0,1]
	v_pk_add_f32 v[40:41], v[16:17], v[2:3] op_sel_hi:[1,0] neg_lo:[0,1] neg_hi:[0,1]
	v_pk_add_f32 v[34:35], v[34:35], v[2:3] op_sel_hi:[1,0] neg_lo:[0,1] neg_hi:[0,1]
	v_pk_add_f32 v[36:37], v[32:33], v[2:3] op_sel_hi:[1,0] neg_lo:[0,1] neg_hi:[0,1]
	v_pk_add_f32 v[30:31], v[30:31], v[2:3] op_sel_hi:[1,0] neg_lo:[0,1] neg_hi:[0,1]
	v_pk_add_f32 v[32:33], v[54:55], v[2:3] op_sel_hi:[1,0] neg_lo:[0,1] neg_hi:[0,1]
	v_pk_add_f32 v[26:27], v[26:27], v[2:3] op_sel_hi:[1,0] neg_lo:[0,1] neg_hi:[0,1]
	v_pk_add_f32 v[28:29], v[28:29], v[2:3] op_sel_hi:[1,0] neg_lo:[0,1] neg_hi:[0,1]
	v_pk_add_f32 v[20:21], v[52:53], v[2:3] op_sel_hi:[1,0] neg_lo:[0,1] neg_hi:[0,1]
	v_pk_add_f32 v[22:23], v[22:23], v[2:3] op_sel_hi:[1,0] neg_lo:[0,1] neg_hi:[0,1]
	v_pk_add_f32 v[16:17], v[50:51], v[2:3] op_sel_hi:[1,0] neg_lo:[0,1] neg_hi:[0,1]
	v_pk_add_f32 v[18:19], v[24:25], v[2:3] op_sel_hi:[1,0] neg_lo:[0,1] neg_hi:[0,1]
	v_fma_f32 v2, v56, v56, 0
	v_fmac_f32_e32 v2, v57, v57
	v_fmac_f32_e32 v2, v58, v58
	v_fmac_f32_e32 v2, v59, v59
	v_fmac_f32_e32 v2, v42, v42
	v_fmac_f32_e32 v2, v43, v43
	v_fmac_f32_e32 v2, v44, v44
	v_fmac_f32_e32 v2, v45, v45
	v_fmac_f32_e32 v2, v38, v38
	v_fmac_f32_e32 v2, v39, v39
	v_fmac_f32_e32 v2, v40, v40
	v_fmac_f32_e32 v2, v41, v41
	v_fmac_f32_e32 v2, v34, v34
	v_fmac_f32_e32 v2, v35, v35
	v_fmac_f32_e32 v2, v36, v36
	v_fmac_f32_e32 v2, v37, v37
	v_fmac_f32_e32 v2, v30, v30
	v_fmac_f32_e32 v2, v31, v31
	v_fmac_f32_e32 v2, v32, v32
	v_fmac_f32_e32 v2, v33, v33
	v_fmac_f32_e32 v2, v26, v26
	v_fmac_f32_e32 v2, v27, v27
	v_fmac_f32_e32 v2, v28, v28
	v_fmac_f32_e32 v2, v29, v29
	v_fmac_f32_e32 v2, v20, v20
	v_fmac_f32_e32 v2, v21, v21
	v_fmac_f32_e32 v2, v22, v22
	v_fmac_f32_e32 v2, v23, v23
	v_fmac_f32_e32 v2, v16, v16
	v_fmac_f32_e32 v2, v17, v17
	v_fmac_f32_e32 v2, v18, v18
	v_fmac_f32_e32 v2, v19, v19
	ds_swizzle_b32 v24, v2 offset:swizzle(SWAP,1)
	v_cndmask_b32_e64 v25, 0, 1, s[48:49]
	v_cmp_ne_u32_e64 s[40:41], 1, v25
	v_lshl_add_u64 v[14:15], v[14:15], 2, s[16:17]
	s_waitcnt lgkmcnt(0)
	v_add_f32_e32 v2, v2, v24
	ds_swizzle_b32 v24, v2 offset:swizzle(SWAP,2)
	s_waitcnt lgkmcnt(0)
	v_add_f32_e32 v2, v2, v24
	ds_swizzle_b32 v24, v2 offset:swizzle(SWAP,4)
	s_waitcnt lgkmcnt(0)
	v_add_f32_e32 v2, v2, v24
	ds_swizzle_b32 v24, v2 offset:swizzle(SWAP,8)
	s_waitcnt lgkmcnt(0)
	v_add_f32_e32 v2, v2, v24
	ds_swizzle_b32 v24, v2 offset:swizzle(SWAP,16)
	s_waitcnt lgkmcnt(0)
	v_add_f32_e32 v2, v2, v24
	v_mov_b32_e32 v24, v2
	s_nop 1
	v_permlane32_swap_b32_e32 v2, v24
	v_add_f32_e32 v2, v2, v24
	v_fmamk_f32 v2, v2, 0x3a000000, v200
	v_mul_f32_e32 v24, 0x4b800000, v2
	v_cmp_gt_f32_e64 s[42:43], s33, v2
	s_nop 1
	v_cndmask_b32_e64 v2, v2, v24, s[42:43]
	v_rsq_f32_e32 v2, v2
	s_nop 0
	v_mul_f32_e32 v24, 0x45800000, v2
	v_cndmask_b32_e64 v24, v2, v24, s[42:43]
	v_mov_b32_e32 v25, v24
	global_load_dwordx4 v[220:223], v[12:13], off offset:1024
	global_load_dwordx4 v[236:239], v[10:11], off offset:1024
	global_load_dwordx4 v[224:227], v[12:13], off offset:2048
	global_load_dwordx4 v[240:243], v[10:11], off offset:2048
	global_load_dwordx4 v[228:231], v[12:13], off offset:3072
	global_load_dwordx4 v[244:247], v[10:11], off offset:3072
	v_add_co_u32_e32 v250, vcc, 0x1000, v12
	s_nop 1
	v_addc_co_u32_e32 v251, vcc, 0, v13, vcc
	v_add_co_u32_e32 v252, vcc, 0x1000, v10
	s_nop 1
	v_addc_co_u32_e32 v253, vcc, 0, v11, vcc
	v_add_co_u32_e32 v254, vcc, 0x1000, v14
	s_nop 1
	v_addc_co_u32_e32 v255, vcc, 0, v15, vcc
	v_pk_mul_f32 v[50:51], v[56:57], v[24:25]
	v_pk_mul_f32 v[52:53], v[58:59], v[24:25]
	s_waitcnt vmcnt(6)
	v_pk_fma_f32 v[4:5], v[4:5], v[50:51], v[46:47]
	v_pk_fma_f32 v[6:7], v[6:7], v[52:53], v[48:49]
	s_and_b64 vcc, exec, s[40:41]
	s_cbranch_vccnz .Lln12_skip0
	global_store_dwordx4 v[14:15], v[4:7], off
; #define GAS __attribute__((address_space(1)))
; __device__ __forceinline__ unsigned cvtpk(float lo, float hi) { return __builtin_bit_cast(unsigned, __builtin_convertvector(f32x2_cv{lo, hi}, bf16x2_cv)); }
; __device__ __forceinline__ void peer_gather_f4p(const float* X, const int* __restrict__ IDX, const float* __restrict__ G, ...
;     ...
; #pragma unroll
;         for (int j = 0; j < 8; ++j) {
;             const int col = 256 * j + lane * 4;
;             const f32x4 g4 = *(const GAS f32x4*)((const GAS float*)gl_ + col), b4 = *(const GAS f32x4*)((const GAS float*)bl_ + col);
;             f32x4 o4;
;             o4[0] = (acc[2 * j][0] - mu) * rstd * g4[0] + b4[0]; o4[1] = (acc[2 * j][1] - mu) * rstd * g4[1] + b4[1];
;             o4[2] = (acc[2 * j + 1][0] - mu) * rstd * g4[2] + b4[2]; o4[3] = (acc[2 * j + 1][1] - mu) * rstd * g4[3] + b4[3];
;             if (!RES_BF16 || dst != nullptr) *(GAS f32x4*)((GAS float*)dst + (size_t)row * D + col) = o4;
;             *(GAS u32x2*)((GAS bf16_t*)xbout + (size_t)row * D + col) = u32x2{cvtpk(o4[0], o4[1]), cvtpk(o4[2], o4[3])};
;         }
.Lln12_skip0:
	v_cvt_pk_bf16_f32 v54, v4, v5
	v_cvt_pk_bf16_f32 v55, v6, v7
	global_store_dwordx2 v[8:9], v[54:55], off
	global_load_dwordx4 v[216:219], v[250:251], off
	global_load_dwordx4 v[232:235], v[252:253], off
	v_pk_mul_f32 v[50:51], v[42:43], v[24:25]
	v_pk_mul_f32 v[52:53], v[44:45], v[24:25]
	s_waitcnt vmcnt(7)
	v_pk_fma_f32 v[4:5], v[220:221], v[50:51], v[236:237]
	v_pk_fma_f32 v[6:7], v[222:223], v[52:53], v[238:239]
	s_and_b64 vcc, exec, s[40:41]
	s_cbranch_vccnz .Lln12_skip1
	global_store_dwordx4 v[14:15], v[4:7], off offset:1024
.Lln12_skip1:
	v_cvt_pk_bf16_f32 v214, v4, v5
	v_cvt_pk_bf16_f32 v215, v6, v7
	global_store_dwordx2 v[8:9], v[214:215], off offset:512
	global_load_dwordx4 v[220:223], v[250:251], off offset:1024
	global_load_dwordx4 v[236:239], v[252:253], off offset:1024
	v_pk_mul_f32 v[50:51], v[38:39], v[24:25]
	v_pk_mul_f32 v[52:53], v[40:41], v[24:25]
	s_waitcnt vmcnt(8)
	v_pk_fma_f32 v[4:5], v[224:225], v[50:51], v[240:241]
	v_pk_fma_f32 v[6:7], v[226:227], v[52:53], v[242:243]
	s_and_b64 vcc, exec, s[40:41]
	s_cbranch_vccnz .Lln12_skip2
	global_store_dwordx4 v[14:15], v[4:7], off offset:2048
.Lln12_skip2:
	v_cvt_pk_bf16_f32 v54, v4, v5
	v_cvt_pk_bf16_f32 v55, v6, v7
	global_store_dwordx2 v[8:9], v[54:55], off offset:1024
	global_load_dwordx4 v[224:227], v[250:251], off offset:2048
	global_load_dwordx4 v[240:243], v[252:253], off offset:2048
	v_pk_mul_f32 v[50:51], v[34:35], v[24:25]
	v_pk_mul_f32 v[52:53], v[36:37], v[24:25]
	s_waitcnt vmcnt(9)
	v_pk_fma_f32 v[4:5], v[228:229], v[50:51], v[244:245]
	v_pk_fma_f32 v[6:7], v[230:231], v[52:53], v[246:247]
	s_and_b64 vcc, exec, s[40:41]
	s_cbranch_vccnz .Lln12_skip3
	global_store_dwordx4 v[14:15], v[4:7], off offset:3072
.Lln12_skip3:
	v_cvt_pk_bf16_f32 v214, v4, v5
	v_cvt_pk_bf16_f32 v215, v6, v7
	global_store_dwordx2 v[8:9], v[214:215], off offset:1536
	global_load_dwordx4 v[228:231], v[250:251], off offset:3072
	global_load_dwordx4 v[244:247], v[252:253], off offset:3072
	v_pk_mul_f32 v[50:51], v[30:31], v[24:25]
	v_pk_mul_f32 v[52:53], v[32:33], v[24:25]
	s_waitcnt vmcnt(9)
	v_pk_fma_f32 v[4:5], v[216:217], v[50:51], v[232:233]
	v_pk_fma_f32 v[6:7], v[218:219], v[52:53], v[234:235]
	s_and_b64 vcc, exec, s[40:41]
	s_cbranch_vccnz .Lln12_skip4
	global_store_dwordx4 v[254:255], v[4:7], off
.Lln12_skip4:
	v_cvt_pk_bf16_f32 v54, v4, v5
	v_cvt_pk_bf16_f32 v55, v6, v7
	global_store_dwordx2 v[8:9], v[54:55], off offset:2048
	v_pk_mul_f32 v[50:51], v[26:27], v[24:25]
	v_pk_mul_f32 v[52:53], v[28:29], v[24:25]
	s_waitcnt vmcnt(7)
	v_pk_fma_f32 v[4:5], v[220:221], v[50:51], v[236:237]
	v_pk_fma_f32 v[6:7], v[222:223], v[52:53], v[238:239]
	s_and_b64 vcc, exec, s[40:41]
	s_cbranch_vccnz .Lln12_skip5
	global_store_dwordx4 v[254:255], v[4:7], off offset:1024
.Lln12_skip5:
	v_cvt_pk_bf16_f32 v214, v4, v5
	v_cvt_pk_bf16_f32 v215, v6, v7
	global_store_dwordx2 v[8:9], v[214:215], off offset:2560
	v_pk_mul_f32 v[50:51], v[20:21], v[24:25]
	v_pk_mul_f32 v[52:53], v[22:23], v[24:25]
	s_waitcnt vmcnt(5)
	v_pk_fma_f32 v[4:5], v[224:225], v[50:51], v[240:241]
	v_pk_fma_f32 v[6:7], v[226:227], v[52:53], v[242:243]
	s_and_b64 vcc, exec, s[40:41]
	s_cbranch_vccnz .Lln12_skip6
	global_store_dwordx4 v[254:255], v[4:7], off offset:2048
.Lln12_skip6:
	v_cvt_pk_bf16_f32 v54, v4, v5
	v_cvt_pk_bf16_f32 v55, v6, v7
	global_store_dwordx2 v[8:9], v[54:55], off offset:3072
	v_pk_mul_f32 v[50:51], v[16:17], v[24:25]
	v_pk_mul_f32 v[52:53], v[18:19], v[24:25]
	s_waitcnt vmcnt(3)
	v_pk_fma_f32 v[4:5], v[228:229], v[50:51], v[244:245]
	v_pk_fma_f32 v[6:7], v[230:231], v[52:53], v[246:247]
	s_and_b64 vcc, exec, s[40:41]
	s_cbranch_vccnz .Lln12_skip7
	global_store_dwordx4 v[254:255], v[4:7], off offset:3072
.Lln12_skip7:
	s_nop 1
	s_branch .LBB0_1245

; __global__ void __launch_bounds__(NTHR, 2) fwd_kernel(Params p_unused) {
	.amdhsa_kernel _ZN12_GLOBAL__N_110fwd_kernelENS_6ParamsE
		.amdhsa_group_segment_fixed_size 0
		.amdhsa_private_segment_fixed_size 0
		.amdhsa_kernarg_size 192
		.amdhsa_user_sgpr_count 2
		.amdhsa_user_sgpr_dispatch_ptr 0
		.amdhsa_user_sgpr_queue_ptr 0
		.amdhsa_user_sgpr_kernarg_segment_ptr 1
		.amdhsa_user_sgpr_dispatch_id 0
		.amdhsa_user_sgpr_kernarg_preload_length 0
		.amdhsa_user_sgpr_kernarg_preload_offset 0
		.amdhsa_user_sgpr_private_segment_size 0
		.amdhsa_uses_dynamic_stack 0
		.amdhsa_enable_private_segment 0
		.amdhsa_system_sgpr_workgroup_id_x 1
		.amdhsa_system_sgpr_workgroup_id_y 0
		.amdhsa_system_sgpr_workgroup_id_z 0
		.amdhsa_system_sgpr_workgroup_info 0
		.amdhsa_system_vgpr_workitem_id 0
		.amdhsa_next_free_vgpr 256
		.amdhsa_next_free_sgpr 100
		.amdhsa_accum_offset 256
		.amdhsa_reserve_vcc 1
		.amdhsa_float_round_mode_32 0
		.amdhsa_float_round_mode_16_64 0
		.amdhsa_float_denorm_mode_32 3
		.amdhsa_float_denorm_mode_16_64 3
		.amdhsa_dx10_clamp 1
		.amdhsa_ieee_mode 1
		.amdhsa_fp16_overflow 0
		.amdhsa_tg_split 0
		.amdhsa_exception_fp_ieee_invalid_op 0
		.amdhsa_exception_fp_denorm_src 0
		.amdhsa_exception_fp_ieee_div_zero 0
		.amdhsa_exception_fp_ieee_overflow 0
		.amdhsa_exception_fp_ieee_underflow 0
		.amdhsa_exception_fp_ieee_inexact 0
		.amdhsa_exception_int_div_zero 0
	.end_amdhsa_kernel

; __global__ void __launch_bounds__(NTHR, 2) fwd_kernel(Params p_unused) {
amdhsa.kernels:
  - .agpr_count:     0
    .args:
      - .offset:         0
        .size:           192
        .value_kind:     by_value
    .group_segment_fixed_size: 0
    .kernarg_segment_align: 8
    .kernarg_segment_size: 192
    .language:       OpenCL C
    .language_version:
      - 2
      - 0
    .max_flat_workgroup_size: 512
    .name:           _ZN12_GLOBAL__N_110fwd_kernelENS_6ParamsE
    .private_segment_fixed_size: 0
    .sgpr_count:     106
    .sgpr_spill_count: 192
    .symbol:         _ZN12_GLOBAL__N_110fwd_kernelENS_6ParamsE.kd
    .uniform_work_group_size: 1
    .uses_dynamic_stack: false
    .vgpr_count:     256
    .vgpr_spill_count: 0
    .wavefront_size: 64
